# deferred x_mid stores: v92 with the fused GEMM-out epilogue's x_mid stores issued after the norm2 partial-sum store so the grid-barrier arrival is not held behind them
# baseline (speedup 1.0000x reference)
.Lf2_nosync:
	s_barrier
	s_and_b32 s9, s72, 7
	s_lshl_b32 s9, s9, 3
	s_bfe_u32 s11, s72, 0x30003
	s_or_b32 s9, s9, s11
	s_lshr_b32 s10, s72, 6
	v_and_b32_e32 v234, 15, v233
	v_lshrrev_b32_e32 v235, 4, v233
	s_and_b32 s11, s8, 3
	s_lshr_b32 s12, s8, 2
	s_lshl_b32 s12, s12, 6
	v_add_u32_e32 v236, s12, v234
	s_lshl_b32 s12, s11, 5
	v_lshl_add_u32 v237, v235, 2, s12
	v_lshl_add_u32 v230, v236, 4, v235
	s_lshl_b32 s12, s11, 2
	v_add_u32_e32 v230, s12, v230
	v_lshlrev_b32_e32 v230, 2, v230
	s_lshl_b32 s12, s10, 8
	v_add_u32_e32 v229, s12, v237
	v_lshlrev_b32_e32 v229, 2, v229
	s_lshl_b32 s12, s9, 8
	v_add_u32_e32 v228, s12, v236
	v_lshl_add_u32 v228, v228, 12, v229
	v_lshrrev_b32_e32 v231, 1, v228
	s_sub_u32 s0, s0, 0x2000000
	s_subb_u32 s1, s1, 0
	s_cmp_lt_u32 s9, 32
	s_cselect_b32 s46, s46, s0
	s_cselect_b32 s47, s47, s1
	s_sub_u32 s11, s9, 32
	s_lshr_b32 s11, s11, 4
	s_add_u32 s11, s11, 1
	s_cmp_lt_u32 s9, 32
	s_cselect_b32 s11, 0, s11
	s_mul_i32 s11, s11, 0x6000
	s_add_u32 s11, s40, s11
	s_addc_u32 s12, s41, 0
	s_add_u32 s48, s11, 0x2000
	s_addc_u32 s49, s12, 0
	s_add_u32 s60, s11, 0x3000
	s_addc_u32 s61, s12, 0
	s_add_u32 s58, s11, 0x4000
	s_addc_u32 s59, s12, 0
	s_add_u32 s52, s40, 0xf984000
	s_addc_u32 s53, s41, 0
	s_add_u32 s54, s40, 0x1380000
	s_addc_u32 s55, s41, 0
	global_load_dwordx4 v[144:147], v229, s[48:49]
	global_load_dwordx4 v[148:151], v229, s[48:49] offset:64
	global_load_dwordx4 v[152:155], v229, s[48:49] offset:512
	global_load_dwordx4 v[156:159], v229, s[48:49] offset:576
	v_and_b32_e32 v238, 1, v235
	v_lshlrev_b32_e32 v238, 5, v238
	v_lshrrev_b32_e32 v239, 1, v235
	v_lshl_add_u32 v238, v239, 4, v238
	v_lshlrev_b32_e32 v239, 3, v235
	v_sub_u32_e32 v238, v238, v239
	v_add_u32_e32 v231, v231, v238
	global_load_dwordx4 v[160:163], v229, s[56:57]
	global_load_dwordx4 v[164:167], v229, s[56:57] offset:64
	global_load_dwordx4 v[168:171], v229, s[56:57] offset:512
	global_load_dwordx4 v[172:175], v229, s[56:57] offset:576
	global_load_dwordx4 v[80:83], v229, s[58:59]
	global_load_dwordx4 v[84:87], v229, s[58:59] offset:64
	global_load_dwordx4 v[88:91], v229, s[58:59] offset:512
	global_load_dwordx4 v[92:95], v229, s[58:59] offset:576
	s_add_u32 s50, s46, 0x0
	s_addc_u32 s51, s47, 0
	global_load_dwordx4 v[180:183], v228, s[50:51]
	global_load_dwordx4 v[184:187], v228, s[50:51] offset:64
	global_load_dwordx4 v[188:191], v228, s[50:51] offset:512
	global_load_dwordx4 v[192:195], v228, s[50:51] offset:576
	s_add_u32 s50, s46, 0x10000
	s_addc_u32 s51, s47, 0
	global_load_dwordx4 v[196:199], v228, s[50:51]
	global_load_dwordx4 v[200:203], v228, s[50:51] offset:64
	global_load_dwordx4 v[204:207], v228, s[50:51] offset:512
	global_load_dwordx4 v[208:211], v228, s[50:51] offset:576
	s_waitcnt vmcnt(4)
	v_pk_add_f32 v[80:81], v[80:81], 1.0 op_sel_hi:[1,0]
	v_pk_add_f32 v[82:83], v[82:83], 1.0 op_sel_hi:[1,0]
	v_pk_add_f32 v[84:85], v[84:85], 1.0 op_sel_hi:[1,0]
	v_pk_add_f32 v[86:87], v[86:87], 1.0 op_sel_hi:[1,0]
	v_pk_add_f32 v[88:89], v[88:89], 1.0 op_sel_hi:[1,0]
	v_pk_add_f32 v[90:91], v[90:91], 1.0 op_sel_hi:[1,0]
	v_pk_add_f32 v[92:93], v[92:93], 1.0 op_sel_hi:[1,0]
	v_pk_add_f32 v[94:95], v[94:95], 1.0 op_sel_hi:[1,0]
	v_pk_fma_f32 v[140:141], v[140:141], v[144:145], v[180:181]
	v_pk_fma_f32 v[142:143], v[142:143], v[146:147], v[182:183]
	v_pk_fma_f32 v[136:137], v[136:137], v[148:149], v[184:185]
	v_pk_fma_f32 v[138:139], v[138:139], v[150:151], v[186:187]
	v_pk_fma_f32 v[132:133], v[132:133], v[152:153], v[188:189]
	v_pk_fma_f32 v[134:135], v[134:135], v[154:155], v[190:191]
	v_pk_fma_f32 v[128:129], v[128:129], v[156:157], v[192:193]
	v_pk_fma_f32 v[130:131], v[130:131], v[158:159], v[194:195]
	v_mul_f32_e32 v232, v140, v140
	v_fmac_f32_e32 v232, v141, v141
	v_fmac_f32_e32 v232, v142, v142
	v_fmac_f32_e32 v232, v143, v143
	v_fmac_f32_e32 v232, v136, v136
	v_fmac_f32_e32 v232, v137, v137
	v_fmac_f32_e32 v232, v138, v138
	v_fmac_f32_e32 v232, v139, v139
	v_fmac_f32_e32 v232, v132, v132
	v_fmac_f32_e32 v232, v133, v133
	v_fmac_f32_e32 v232, v134, v134
	v_fmac_f32_e32 v232, v135, v135
	v_fmac_f32_e32 v232, v128, v128
	v_fmac_f32_e32 v232, v129, v129
	v_fmac_f32_e32 v232, v130, v130
	v_fmac_f32_e32 v232, v131, v131
	ds_write_b32 v230, v232 offset:0
	s_add_u32 s50, s46, 0x20000
	s_addc_u32 s51, s47, 0
	global_load_dwordx4 v[180:183], v228, s[50:51]
	global_load_dwordx4 v[184:187], v228, s[50:51] offset:64
	global_load_dwordx4 v[188:191], v228, s[50:51] offset:512
	global_load_dwordx4 v[192:195], v228, s[50:51] offset:576
	s_waitcnt vmcnt(4)
	v_pk_fma_f32 v[124:125], v[124:125], v[144:145], v[196:197]
	v_pk_fma_f32 v[126:127], v[126:127], v[146:147], v[198:199]
	v_pk_fma_f32 v[120:121], v[120:121], v[148:149], v[200:201]
	v_pk_fma_f32 v[122:123], v[122:123], v[150:151], v[202:203]
	v_pk_fma_f32 v[116:117], v[116:117], v[152:153], v[204:205]
	v_pk_fma_f32 v[118:119], v[118:119], v[154:155], v[206:207]
	v_pk_fma_f32 v[112:113], v[112:113], v[156:157], v[208:209]
	v_pk_fma_f32 v[114:115], v[114:115], v[158:159], v[210:211]
	v_mul_f32_e32 v232, v124, v124
	v_fmac_f32_e32 v232, v125, v125
	v_fmac_f32_e32 v232, v126, v126
	v_fmac_f32_e32 v232, v127, v127
	v_fmac_f32_e32 v232, v120, v120
	v_fmac_f32_e32 v232, v121, v121
	v_fmac_f32_e32 v232, v122, v122
	v_fmac_f32_e32 v232, v123, v123
	v_fmac_f32_e32 v232, v116, v116
	v_fmac_f32_e32 v232, v117, v117
	v_fmac_f32_e32 v232, v118, v118
	v_fmac_f32_e32 v232, v119, v119
	v_fmac_f32_e32 v232, v112, v112
	v_fmac_f32_e32 v232, v113, v113
	v_fmac_f32_e32 v232, v114, v114
	v_fmac_f32_e32 v232, v115, v115
	ds_write_b32 v230, v232 offset:1024
	s_add_u32 s50, s46, 0x30000
	s_addc_u32 s51, s47, 0
	global_load_dwordx4 v[196:199], v228, s[50:51]
	global_load_dwordx4 v[200:203], v228, s[50:51] offset:64
	global_load_dwordx4 v[204:207], v228, s[50:51] offset:512
	global_load_dwordx4 v[208:211], v228, s[50:51] offset:576
	s_waitcnt vmcnt(4)
	v_pk_fma_f32 v[108:109], v[108:109], v[144:145], v[180:181]
	v_pk_fma_f32 v[110:111], v[110:111], v[146:147], v[182:183]
	v_pk_fma_f32 v[104:105], v[104:105], v[148:149], v[184:185]
	v_pk_fma_f32 v[106:107], v[106:107], v[150:151], v[186:187]
	v_pk_fma_f32 v[100:101], v[100:101], v[152:153], v[188:189]
	v_pk_fma_f32 v[102:103], v[102:103], v[154:155], v[190:191]
	v_pk_fma_f32 v[96:97], v[96:97], v[156:157], v[192:193]
	v_pk_fma_f32 v[98:99], v[98:99], v[158:159], v[194:195]
	v_mul_f32_e32 v232, v108, v108
	v_fmac_f32_e32 v232, v109, v109
	v_fmac_f32_e32 v232, v110, v110
	v_fmac_f32_e32 v232, v111, v111
	v_fmac_f32_e32 v232, v104, v104
	v_fmac_f32_e32 v232, v105, v105
	v_fmac_f32_e32 v232, v106, v106
	v_fmac_f32_e32 v232, v107, v107
	v_fmac_f32_e32 v232, v100, v100
	v_fmac_f32_e32 v232, v101, v101
	v_fmac_f32_e32 v232, v102, v102
	v_fmac_f32_e32 v232, v103, v103
	v_fmac_f32_e32 v232, v96, v96
	v_fmac_f32_e32 v232, v97, v97
	v_fmac_f32_e32 v232, v98, v98
	v_fmac_f32_e32 v232, v99, v99
	ds_write_b32 v230, v232 offset:2048
	s_add_u32 s50, s46, 0x80000
	s_addc_u32 s51, s47, 0
	global_load_dwordx4 v[180:183], v228, s[50:51]
	global_load_dwordx4 v[184:187], v228, s[50:51] offset:64
	global_load_dwordx4 v[188:191], v228, s[50:51] offset:512
	global_load_dwordx4 v[192:195], v228, s[50:51] offset:576
	s_waitcnt vmcnt(4)
	v_pk_fma_f32 v[76:77], v[76:77], v[144:145], v[196:197]
	v_pk_fma_f32 v[78:79], v[78:79], v[146:147], v[198:199]
	v_pk_fma_f32 v[72:73], v[72:73], v[148:149], v[200:201]
	v_pk_fma_f32 v[74:75], v[74:75], v[150:151], v[202:203]
	v_pk_fma_f32 v[68:69], v[68:69], v[152:153], v[204:205]
	v_pk_fma_f32 v[70:71], v[70:71], v[154:155], v[206:207]
	v_pk_fma_f32 v[64:65], v[64:65], v[156:157], v[208:209]
	v_pk_fma_f32 v[66:67], v[66:67], v[158:159], v[210:211]
	v_mul_f32_e32 v232, v76, v76
	v_fmac_f32_e32 v232, v77, v77
	v_fmac_f32_e32 v232, v78, v78
	v_fmac_f32_e32 v232, v79, v79
	v_fmac_f32_e32 v232, v72, v72
	v_fmac_f32_e32 v232, v73, v73
	v_fmac_f32_e32 v232, v74, v74
	v_fmac_f32_e32 v232, v75, v75
	v_fmac_f32_e32 v232, v68, v68
	v_fmac_f32_e32 v232, v69, v69
	v_fmac_f32_e32 v232, v70, v70
	v_fmac_f32_e32 v232, v71, v71
	v_fmac_f32_e32 v232, v64, v64
	v_fmac_f32_e32 v232, v65, v65
	v_fmac_f32_e32 v232, v66, v66
	v_fmac_f32_e32 v232, v67, v67
	ds_write_b32 v230, v232 offset:3072
	s_add_u32 s50, s46, 0x90000
	s_addc_u32 s51, s47, 0
	global_load_dwordx4 v[196:199], v228, s[50:51]
	global_load_dwordx4 v[200:203], v228, s[50:51] offset:64
	global_load_dwordx4 v[204:207], v228, s[50:51] offset:512
	global_load_dwordx4 v[208:211], v228, s[50:51] offset:576
	s_waitcnt vmcnt(4)
	v_pk_fma_f32 v[60:61], v[60:61], v[144:145], v[180:181]
	v_pk_fma_f32 v[62:63], v[62:63], v[146:147], v[182:183]
	v_pk_fma_f32 v[56:57], v[56:57], v[148:149], v[184:185]
	v_pk_fma_f32 v[58:59], v[58:59], v[150:151], v[186:187]
	v_pk_fma_f32 v[52:53], v[52:53], v[152:153], v[188:189]
	v_pk_fma_f32 v[54:55], v[54:55], v[154:155], v[190:191]
	v_pk_fma_f32 v[48:49], v[48:49], v[156:157], v[192:193]
	v_pk_fma_f32 v[50:51], v[50:51], v[158:159], v[194:195]
	v_mul_f32_e32 v232, v60, v60
	v_fmac_f32_e32 v232, v61, v61
	v_fmac_f32_e32 v232, v62, v62
	v_fmac_f32_e32 v232, v63, v63
	v_fmac_f32_e32 v232, v56, v56
	v_fmac_f32_e32 v232, v57, v57
	v_fmac_f32_e32 v232, v58, v58
	v_fmac_f32_e32 v232, v59, v59
	v_fmac_f32_e32 v232, v52, v52
	v_fmac_f32_e32 v232, v53, v53
	v_fmac_f32_e32 v232, v54, v54
	v_fmac_f32_e32 v232, v55, v55
	v_fmac_f32_e32 v232, v48, v48
	v_fmac_f32_e32 v232, v49, v49
	v_fmac_f32_e32 v232, v50, v50
	v_fmac_f32_e32 v232, v51, v51
	ds_write_b32 v230, v232 offset:8192
	s_add_u32 s50, s46, 0xa0000
	s_addc_u32 s51, s47, 0
	global_load_dwordx4 v[180:183], v228, s[50:51]
	global_load_dwordx4 v[184:187], v228, s[50:51] offset:64
	global_load_dwordx4 v[188:191], v228, s[50:51] offset:512
	global_load_dwordx4 v[192:195], v228, s[50:51] offset:576
	s_waitcnt vmcnt(4)
	v_pk_fma_f32 v[44:45], v[44:45], v[144:145], v[196:197]
	v_pk_fma_f32 v[46:47], v[46:47], v[146:147], v[198:199]
	v_pk_fma_f32 v[40:41], v[40:41], v[148:149], v[200:201]
	v_pk_fma_f32 v[42:43], v[42:43], v[150:151], v[202:203]
	v_pk_fma_f32 v[36:37], v[36:37], v[152:153], v[204:205]
	v_pk_fma_f32 v[38:39], v[38:39], v[154:155], v[206:207]
	v_pk_fma_f32 v[32:33], v[32:33], v[156:157], v[208:209]
	v_pk_fma_f32 v[34:35], v[34:35], v[158:159], v[210:211]
	v_mul_f32_e32 v232, v44, v44
	v_fmac_f32_e32 v232, v45, v45
	v_fmac_f32_e32 v232, v46, v46
	v_fmac_f32_e32 v232, v47, v47
	v_fmac_f32_e32 v232, v40, v40
	v_fmac_f32_e32 v232, v41, v41
	v_fmac_f32_e32 v232, v42, v42
	v_fmac_f32_e32 v232, v43, v43
	v_fmac_f32_e32 v232, v36, v36
	v_fmac_f32_e32 v232, v37, v37
	v_fmac_f32_e32 v232, v38, v38
	v_fmac_f32_e32 v232, v39, v39
	v_fmac_f32_e32 v232, v32, v32
	v_fmac_f32_e32 v232, v33, v33
	v_fmac_f32_e32 v232, v34, v34
	v_fmac_f32_e32 v232, v35, v35
	ds_write_b32 v230, v232 offset:9216
	s_add_u32 s50, s46, 0xb0000
	s_addc_u32 s51, s47, 0
	global_load_dwordx4 v[196:199], v228, s[50:51]
	global_load_dwordx4 v[200:203], v228, s[50:51] offset:64
	global_load_dwordx4 v[204:207], v228, s[50:51] offset:512
	global_load_dwordx4 v[208:211], v228, s[50:51] offset:576
	s_waitcnt vmcnt(4)
	v_pk_fma_f32 v[28:29], v[28:29], v[144:145], v[180:181]
	v_pk_fma_f32 v[30:31], v[30:31], v[146:147], v[182:183]
	v_pk_fma_f32 v[24:25], v[24:25], v[148:149], v[184:185]
	v_pk_fma_f32 v[26:27], v[26:27], v[150:151], v[186:187]
	v_pk_fma_f32 v[12:13], v[12:13], v[152:153], v[188:189]
	v_pk_fma_f32 v[14:15], v[14:15], v[154:155], v[190:191]
	v_pk_fma_f32 v[8:9], v[8:9], v[156:157], v[192:193]
	v_pk_fma_f32 v[10:11], v[10:11], v[158:159], v[194:195]
	v_mul_f32_e32 v232, v28, v28
	v_fmac_f32_e32 v232, v29, v29
	v_fmac_f32_e32 v232, v30, v30
	v_fmac_f32_e32 v232, v31, v31
	v_fmac_f32_e32 v232, v24, v24
	v_fmac_f32_e32 v232, v25, v25
	v_fmac_f32_e32 v232, v26, v26
	v_fmac_f32_e32 v232, v27, v27
	v_fmac_f32_e32 v232, v12, v12
	v_fmac_f32_e32 v232, v13, v13
	v_fmac_f32_e32 v232, v14, v14
	v_fmac_f32_e32 v232, v15, v15
	v_fmac_f32_e32 v232, v8, v8
	v_fmac_f32_e32 v232, v9, v9
	v_fmac_f32_e32 v232, v10, v10
	v_fmac_f32_e32 v232, v11, v11
	ds_write_b32 v230, v232 offset:10240
	s_waitcnt vmcnt(0)
	v_pk_fma_f32 v[20:21], v[20:21], v[144:145], v[196:197]
	v_pk_fma_f32 v[22:23], v[22:23], v[146:147], v[198:199]
	v_pk_fma_f32 v[16:17], v[16:17], v[148:149], v[200:201]
	v_pk_fma_f32 v[18:19], v[18:19], v[150:151], v[202:203]
	v_pk_fma_f32 v[4:5], v[4:5], v[152:153], v[204:205]
	v_pk_fma_f32 v[6:7], v[6:7], v[154:155], v[206:207]
	v_pk_fma_f32 v[0:1], v[0:1], v[156:157], v[208:209]
	v_pk_fma_f32 v[2:3], v[2:3], v[158:159], v[210:211]
	v_mul_f32_e32 v232, v20, v20
	v_fmac_f32_e32 v232, v21, v21
	v_fmac_f32_e32 v232, v22, v22
	v_fmac_f32_e32 v232, v23, v23
	v_fmac_f32_e32 v232, v16, v16
	v_fmac_f32_e32 v232, v17, v17
	v_fmac_f32_e32 v232, v18, v18
	v_fmac_f32_e32 v232, v19, v19
	v_fmac_f32_e32 v232, v4, v4
	v_fmac_f32_e32 v232, v5, v5
	v_fmac_f32_e32 v232, v6, v6
	v_fmac_f32_e32 v232, v7, v7
	v_fmac_f32_e32 v232, v0, v0
	v_fmac_f32_e32 v232, v1, v1
	v_fmac_f32_e32 v232, v2, v2
	v_fmac_f32_e32 v232, v3, v3
	ds_write_b32 v230, v232 offset:11264
	global_load_dwordx4 v[144:147], v229, s[60:61]
	global_load_dwordx4 v[148:151], v229, s[60:61] offset:64
	global_load_dwordx4 v[152:155], v229, s[60:61] offset:512
	global_load_dwordx4 v[156:159], v229, s[60:61] offset:576
	s_waitcnt lgkmcnt(0)
	s_barrier
	v_cmp_gt_u32_e32 vcc, 0x100, v177
	s_and_saveexec_b64 s[0:1], vcc
	s_cbranch_execz .Lf2_nored
	v_lshlrev_b32_e32 v233, 6, v177
	ds_read_b128 v[236:239], v233
	ds_read_b128 v[240:243], v233 offset:16
	ds_read_b128 v[244:247], v233 offset:32
	ds_read_b128 v[248:251], v233 offset:48
	s_lshl_b32 s11, s9, 8
	v_add_u32_e32 v234, s11, v177
	v_lshlrev_b32_e32 v234, 4, v234
	s_lshl_b32 s11, s10, 2
	v_add_u32_e32 v234, s11, v234
	s_waitcnt lgkmcnt(0)
	v_add_f32_e32 v236, v236, v237
	v_add_f32_e32 v236, v236, v238
	v_add_f32_e32 v236, v236, v239
	v_add_f32_e32 v236, v236, v240
	v_add_f32_e32 v236, v236, v241
	v_add_f32_e32 v236, v236, v242
	v_add_f32_e32 v236, v236, v243
	v_add_f32_e32 v236, v236, v244
	v_add_f32_e32 v236, v236, v245
	v_add_f32_e32 v236, v236, v246
	v_add_f32_e32 v236, v236, v247
	v_add_f32_e32 v236, v236, v248
	v_add_f32_e32 v236, v236, v249
	v_add_f32_e32 v236, v236, v250
	v_add_f32_e32 v236, v236, v251
	global_store_dword v234, v236, s[52:53]

.LBB0_1258:
	s_cmp_eq_u32 s8, 7
	s_cbranch_scc1 .Lf2_w7a
	s_add_u32 s62, s44, 0x0
	s_addc_u32 s63, s45, 0
	global_store_dwordx4 v228, v[140:143], s[62:63] sc1
	global_store_dwordx4 v228, v[136:139], s[62:63] offset:64 sc1
	global_store_dwordx4 v228, v[132:135], s[62:63] offset:512 sc1
	global_store_dwordx4 v228, v[128:131], s[62:63] offset:576 sc1
	s_add_u32 s62, s44, 0x10000
	s_addc_u32 s63, s45, 0
	global_store_dwordx4 v228, v[124:127], s[62:63] sc1
	global_store_dwordx4 v228, v[120:123], s[62:63] offset:64 sc1
	global_store_dwordx4 v228, v[116:119], s[62:63] offset:512 sc1
	global_store_dwordx4 v228, v[112:115], s[62:63] offset:576 sc1
	s_add_u32 s62, s44, 0x20000
	s_addc_u32 s63, s45, 0
	global_store_dwordx4 v228, v[108:111], s[62:63] sc1
	global_store_dwordx4 v228, v[104:107], s[62:63] offset:64 sc1
	global_store_dwordx4 v228, v[100:103], s[62:63] offset:512 sc1
	global_store_dwordx4 v228, v[96:99], s[62:63] offset:576 sc1
	s_add_u32 s62, s44, 0x30000
	s_addc_u32 s63, s45, 0
	global_store_dwordx4 v228, v[76:79], s[62:63] sc1
	global_store_dwordx4 v228, v[72:75], s[62:63] offset:64 sc1
	global_store_dwordx4 v228, v[68:71], s[62:63] offset:512 sc1
	global_store_dwordx4 v228, v[64:67], s[62:63] offset:576 sc1
	s_add_u32 s62, s44, 0x80000
	s_addc_u32 s63, s45, 0
	global_store_dwordx4 v228, v[60:63], s[62:63] sc1
	global_store_dwordx4 v228, v[56:59], s[62:63] offset:64 sc1
	global_store_dwordx4 v228, v[52:55], s[62:63] offset:512 sc1
	global_store_dwordx4 v228, v[48:51], s[62:63] offset:576 sc1
	s_add_u32 s62, s44, 0x90000
	s_addc_u32 s63, s45, 0
	global_store_dwordx4 v228, v[44:47], s[62:63] sc1
	global_store_dwordx4 v228, v[40:43], s[62:63] offset:64 sc1
	global_store_dwordx4 v228, v[36:39], s[62:63] offset:512 sc1
	global_store_dwordx4 v228, v[32:35], s[62:63] offset:576 sc1
	s_add_u32 s62, s44, 0xa0000
	s_addc_u32 s63, s45, 0
	global_store_dwordx4 v228, v[28:31], s[62:63] sc1
	global_store_dwordx4 v228, v[24:27], s[62:63] offset:64 sc1
	global_store_dwordx4 v228, v[12:15], s[62:63] offset:512 sc1
	global_store_dwordx4 v228, v[8:11], s[62:63] offset:576 sc1
	s_add_u32 s62, s44, 0xb0000
	s_addc_u32 s63, s45, 0
	global_store_dwordx4 v228, v[20:23], s[62:63] sc1
	global_store_dwordx4 v228, v[16:19], s[62:63] offset:64 sc1
	global_store_dwordx4 v228, v[4:7], s[62:63] offset:512 sc1
	global_store_dwordx4 v228, v[0:3], s[62:63] offset:576 sc1
	s_waitcnt vmcnt(32) lgkmcnt(0)
.Lf2_w7a:
	s_nop 0
	s_barrier
	v_cmp_eq_u32_e32 vcc, 0, v177
	s_and_saveexec_b64 s[0:1], vcc
	s_cbranch_execz .Lf2_bar_end_b
	s_add_u32 s98, s98, 1
	v_mov_b32_e32 v237, 0x26c00
	ds_read2_b32 v[238:239], v237 offset1:1
	v_mov_b32_e32 v232, s99
	v_mov_b32_e32 v233, 1
	global_atomic_add v234, v232, v233, s[100:101] sc0
	v_add_u32_e32 v232, 0x1000, v232
	v_mov_b32_e32 v240, 0x2480
	s_waitcnt vmcnt(0) lgkmcnt(0)
	v_add_u32_e32 v234, 1, v234
	v_mul_lo_u32 v235, v238, s98
	v_mul_lo_u32 v239, v239, s98
	v_cmp_eq_u32_e32 vcc, v234, v235
	s_and_saveexec_b64 s[4:5], vcc
	s_cbranch_execz .Lf2_skip_b
	buffer_wbl2 sc1
	s_waitcnt vmcnt(0)
	global_atomic_add v240, v233, s[100:101]
	global_atomic_add v240, v233, s[100:101] offset:256
	global_atomic_add v240, v233, s[100:101] offset:512
	global_atomic_add v240, v233, s[100:101] offset:768
	global_atomic_add v240, v233, s[100:101] offset:1024
	global_atomic_add v240, v233, s[100:101] offset:1280
	global_atomic_add v240, v233, s[100:101] offset:1536
	global_atomic_add v240, v233, s[100:101] offset:1792
	global_atomic_add v240, v233, s[100:101] offset:2048
	global_atomic_add v240, v233, s[100:101] offset:2304
	global_atomic_add v240, v233, s[100:101] offset:2560
	global_atomic_add v240, v233, s[100:101] offset:2816
	global_atomic_add v240, v233, s[100:101] offset:3072
	global_atomic_add v240, v233, s[100:101] offset:3328
	global_atomic_add v240, v233, s[100:101] offset:3584
	global_atomic_add v240, v233, s[100:101] offset:3840

.Lf2_bar_end_b:
	s_or_b64 exec, exec, s[0:1]
	s_barrier
	s_cmp_lg_u32 s8, 7
	s_cbranch_scc1 .Lf2_w7b
	s_add_u32 s62, s44, 0x0
	s_addc_u32 s63, s45, 0
	global_store_dwordx4 v228, v[140:143], s[62:63] sc1
	global_store_dwordx4 v228, v[136:139], s[62:63] offset:64 sc1
	global_store_dwordx4 v228, v[132:135], s[62:63] offset:512 sc1
	global_store_dwordx4 v228, v[128:131], s[62:63] offset:576 sc1
	s_add_u32 s62, s44, 0x10000
	s_addc_u32 s63, s45, 0
	global_store_dwordx4 v228, v[124:127], s[62:63] sc1
	global_store_dwordx4 v228, v[120:123], s[62:63] offset:64 sc1
	global_store_dwordx4 v228, v[116:119], s[62:63] offset:512 sc1
	global_store_dwordx4 v228, v[112:115], s[62:63] offset:576 sc1
	s_add_u32 s62, s44, 0x20000
	s_addc_u32 s63, s45, 0
	global_store_dwordx4 v228, v[108:111], s[62:63] sc1
	global_store_dwordx4 v228, v[104:107], s[62:63] offset:64 sc1
	global_store_dwordx4 v228, v[100:103], s[62:63] offset:512 sc1
	global_store_dwordx4 v228, v[96:99], s[62:63] offset:576 sc1
	s_add_u32 s62, s44, 0x30000
	s_addc_u32 s63, s45, 0
	global_store_dwordx4 v228, v[76:79], s[62:63] sc1
	global_store_dwordx4 v228, v[72:75], s[62:63] offset:64 sc1
	global_store_dwordx4 v228, v[68:71], s[62:63] offset:512 sc1
	global_store_dwordx4 v228, v[64:67], s[62:63] offset:576 sc1
	s_add_u32 s62, s44, 0x80000
	s_addc_u32 s63, s45, 0
	global_store_dwordx4 v228, v[60:63], s[62:63] sc1
	global_store_dwordx4 v228, v[56:59], s[62:63] offset:64 sc1
	global_store_dwordx4 v228, v[52:55], s[62:63] offset:512 sc1
	global_store_dwordx4 v228, v[48:51], s[62:63] offset:576 sc1
	s_add_u32 s62, s44, 0x90000
	s_addc_u32 s63, s45, 0
	global_store_dwordx4 v228, v[44:47], s[62:63] sc1
	global_store_dwordx4 v228, v[40:43], s[62:63] offset:64 sc1
	global_store_dwordx4 v228, v[36:39], s[62:63] offset:512 sc1
	global_store_dwordx4 v228, v[32:35], s[62:63] offset:576 sc1
	s_add_u32 s62, s44, 0xa0000
	s_addc_u32 s63, s45, 0
	global_store_dwordx4 v228, v[28:31], s[62:63] sc1
	global_store_dwordx4 v228, v[24:27], s[62:63] offset:64 sc1
	global_store_dwordx4 v228, v[12:15], s[62:63] offset:512 sc1
	global_store_dwordx4 v228, v[8:11], s[62:63] offset:576 sc1
	s_add_u32 s62, s44, 0xb0000
	s_addc_u32 s63, s45, 0
	global_store_dwordx4 v228, v[20:23], s[62:63] sc1
	global_store_dwordx4 v228, v[16:19], s[62:63] offset:64 sc1
	global_store_dwordx4 v228, v[4:7], s[62:63] offset:512 sc1
	global_store_dwordx4 v228, v[0:3], s[62:63] offset:576 sc1
.Lf2_w7b:
	v_lshrrev_b32_e32 v232, 12, v228
	v_lshlrev_b32_e32 v232, 4, v232
	v_add_u32_e32 v233, 0x0, v232
	v_add_u32_e32 v234, 0x100, v232
	v_add_u32_e32 v235, 0x200, v232
	v_add_u32_e32 v236, 0x300, v232
	v_add_u32_e32 v237, 0x800, v232
	v_add_u32_e32 v238, 0x900, v232
	v_add_u32_e32 v239, 0xa00, v232
	v_add_u32_e32 v240, 0xb00, v232
	global_load_dwordx4 v[180:183], v233, s[52:53]
	global_load_dwordx4 v[184:187], v234, s[52:53]
	global_load_dwordx4 v[188:191], v235, s[52:53]
	global_load_dwordx4 v[192:195], v236, s[52:53]
	global_load_dwordx4 v[196:199], v237, s[52:53]
	global_load_dwordx4 v[200:203], v238, s[52:53]
	global_load_dwordx4 v[204:207], v239, s[52:53]
	global_load_dwordx4 v[208:211], v240, s[52:53]
	s_waitcnt vmcnt(0)
	v_mov_b32_e32 v242, 0x3a800000
	v_mov_b32_e32 v243, 0x358637bd
	v_add_f32_e32 v212, v180, v181
	v_add_f32_e32 v212, v212, v182
	v_add_f32_e32 v212, v212, v183
	v_fma_f32 v212, v212, v242, v243
	v_add_f32_e32 v214, v184, v185
	v_add_f32_e32 v214, v214, v186
	v_add_f32_e32 v214, v214, v187
	v_fma_f32 v214, v214, v242, v243
	v_add_f32_e32 v216, v188, v189
	v_add_f32_e32 v216, v216, v190
	v_add_f32_e32 v216, v216, v191
	v_fma_f32 v216, v216, v242, v243
	v_add_f32_e32 v218, v192, v193
	v_add_f32_e32 v218, v218, v194
	v_add_f32_e32 v218, v218, v195
	v_fma_f32 v218, v218, v242, v243
	v_add_f32_e32 v220, v196, v197
	v_add_f32_e32 v220, v220, v198
	v_add_f32_e32 v220, v220, v199
	v_fma_f32 v220, v220, v242, v243
	v_add_f32_e32 v222, v200, v201
	v_add_f32_e32 v222, v222, v202
	v_add_f32_e32 v222, v222, v203
	v_fma_f32 v222, v222, v242, v243
	v_add_f32_e32 v224, v204, v205
	v_add_f32_e32 v224, v224, v206
	v_add_f32_e32 v224, v224, v207
	v_fma_f32 v224, v224, v242, v243
	v_add_f32_e32 v226, v208, v209
	v_add_f32_e32 v226, v226, v210
	v_add_f32_e32 v226, v226, v211
	v_fma_f32 v226, v226, v242, v243
	v_rsq_f32_e32 v212, v212
	v_rsq_f32_e32 v214, v214
	v_rsq_f32_e32 v216, v216
	v_rsq_f32_e32 v218, v218
	v_rsq_f32_e32 v220, v220
	v_rsq_f32_e32 v222, v222
	v_rsq_f32_e32 v224, v224
	v_rsq_f32_e32 v226, v226
	s_nop 0
	s_add_u32 s62, s54, 0x0
	s_addc_u32 s63, s55, 0
	v_pk_mul_f32 v[140:141], v[140:141], v[212:213] op_sel_hi:[1,0]
	v_pk_mul_f32 v[142:143], v[142:143], v[212:213] op_sel_hi:[1,0]
	v_pk_mul_f32 v[140:141], v[160:161], v[140:141]
	v_pk_mul_f32 v[142:143], v[162:163], v[142:143]
	v_pk_fma_f32 v[140:141], v[80:81], v[140:141], v[144:145]
	v_pk_fma_f32 v[142:143], v[82:83], v[142:143], v[146:147]
	v_pk_mul_f32 v[136:137], v[136:137], v[212:213] op_sel_hi:[1,0]
	v_pk_mul_f32 v[138:139], v[138:139], v[212:213] op_sel_hi:[1,0]
	v_pk_mul_f32 v[136:137], v[164:165], v[136:137]
	v_pk_mul_f32 v[138:139], v[166:167], v[138:139]
	v_pk_fma_f32 v[136:137], v[84:85], v[136:137], v[148:149]
	v_pk_fma_f32 v[138:139], v[86:87], v[138:139], v[150:151]
	v_pk_mul_f32 v[132:133], v[132:133], v[212:213] op_sel_hi:[1,0]
	v_pk_mul_f32 v[134:135], v[134:135], v[212:213] op_sel_hi:[1,0]
	v_pk_mul_f32 v[132:133], v[168:169], v[132:133]
	v_pk_mul_f32 v[134:135], v[170:171], v[134:135]
	v_pk_fma_f32 v[132:133], v[88:89], v[132:133], v[152:153]
	v_pk_fma_f32 v[134:135], v[90:91], v[134:135], v[154:155]
	v_pk_mul_f32 v[128:129], v[128:129], v[212:213] op_sel_hi:[1,0]
	v_pk_mul_f32 v[130:131], v[130:131], v[212:213] op_sel_hi:[1,0]
	v_pk_mul_f32 v[128:129], v[172:173], v[128:129]
	v_pk_mul_f32 v[130:131], v[174:175], v[130:131]
	v_pk_fma_f32 v[128:129], v[92:93], v[128:129], v[156:157]
	v_pk_fma_f32 v[130:131], v[94:95], v[130:131], v[158:159]
	v_cvt_pk_bf16_f32 v236, v140, v141
	v_cvt_pk_bf16_f32 v237, v142, v143
	v_cvt_pk_bf16_f32 v238, v136, v137
	v_cvt_pk_bf16_f32 v239, v138, v139
	s_nop 1
	v_permlane16_swap_b32 v236, v238
	v_permlane16_swap_b32 v237, v239
	global_store_dwordx4 v231, v[236:239], s[62:63] sc1
	v_cvt_pk_bf16_f32 v240, v132, v133
	v_cvt_pk_bf16_f32 v241, v134, v135
	v_cvt_pk_bf16_f32 v242, v128, v129
	v_cvt_pk_bf16_f32 v243, v130, v131
	s_nop 1
	v_permlane16_swap_b32 v240, v242
	v_permlane16_swap_b32 v241, v243
	global_store_dwordx4 v231, v[240:243], s[62:63] offset:256 sc1
	s_add_u32 s62, s54, 0x8000
	s_addc_u32 s63, s55, 0
	v_pk_mul_f32 v[124:125], v[124:125], v[214:215] op_sel_hi:[1,0]
	v_pk_mul_f32 v[126:127], v[126:127], v[214:215] op_sel_hi:[1,0]
	v_pk_mul_f32 v[124:125], v[160:161], v[124:125]
	v_pk_mul_f32 v[126:127], v[162:163], v[126:127]
	v_pk_fma_f32 v[124:125], v[80:81], v[124:125], v[144:145]
	v_pk_fma_f32 v[126:127], v[82:83], v[126:127], v[146:147]
	v_pk_mul_f32 v[120:121], v[120:121], v[214:215] op_sel_hi:[1,0]
	v_pk_mul_f32 v[122:123], v[122:123], v[214:215] op_sel_hi:[1,0]
	v_pk_mul_f32 v[120:121], v[164:165], v[120:121]
	v_pk_mul_f32 v[122:123], v[166:167], v[122:123]
	v_pk_fma_f32 v[120:121], v[84:85], v[120:121], v[148:149]
	v_pk_fma_f32 v[122:123], v[86:87], v[122:123], v[150:151]
	v_pk_mul_f32 v[116:117], v[116:117], v[214:215] op_sel_hi:[1,0]
	v_pk_mul_f32 v[118:119], v[118:119], v[214:215] op_sel_hi:[1,0]
	v_pk_mul_f32 v[116:117], v[168:169], v[116:117]
	v_pk_mul_f32 v[118:119], v[170:171], v[118:119]
	v_pk_fma_f32 v[116:117], v[88:89], v[116:117], v[152:153]
	v_pk_fma_f32 v[118:119], v[90:91], v[118:119], v[154:155]
	v_pk_mul_f32 v[112:113], v[112:113], v[214:215] op_sel_hi:[1,0]
	v_pk_mul_f32 v[114:115], v[114:115], v[214:215] op_sel_hi:[1,0]
	v_pk_mul_f32 v[112:113], v[172:173], v[112:113]
	v_pk_mul_f32 v[114:115], v[174:175], v[114:115]
	v_pk_fma_f32 v[112:113], v[92:93], v[112:113], v[156:157]
	v_pk_fma_f32 v[114:115], v[94:95], v[114:115], v[158:159]
	v_cvt_pk_bf16_f32 v244, v124, v125
	v_cvt_pk_bf16_f32 v245, v126, v127
	v_cvt_pk_bf16_f32 v246, v120, v121
	v_cvt_pk_bf16_f32 v247, v122, v123
	s_nop 1
	v_permlane16_swap_b32 v244, v246
	v_permlane16_swap_b32 v245, v247
	global_store_dwordx4 v231, v[244:247], s[62:63] sc1
	v_cvt_pk_bf16_f32 v248, v116, v117
	v_cvt_pk_bf16_f32 v249, v118, v119
	v_cvt_pk_bf16_f32 v250, v112, v113
	v_cvt_pk_bf16_f32 v251, v114, v115
	s_nop 1
	v_permlane16_swap_b32 v248, v250
	v_permlane16_swap_b32 v249, v251
	global_store_dwordx4 v231, v[248:251], s[62:63] offset:256 sc1
	s_add_u32 s62, s54, 0x10000
	s_addc_u32 s63, s55, 0
	v_pk_mul_f32 v[108:109], v[108:109], v[216:217] op_sel_hi:[1,0]
	v_pk_mul_f32 v[110:111], v[110:111], v[216:217] op_sel_hi:[1,0]
	v_pk_mul_f32 v[108:109], v[160:161], v[108:109]
	v_pk_mul_f32 v[110:111], v[162:163], v[110:111]
	v_pk_fma_f32 v[108:109], v[80:81], v[108:109], v[144:145]
	v_pk_fma_f32 v[110:111], v[82:83], v[110:111], v[146:147]
	v_pk_mul_f32 v[104:105], v[104:105], v[216:217] op_sel_hi:[1,0]
	v_pk_mul_f32 v[106:107], v[106:107], v[216:217] op_sel_hi:[1,0]
	v_pk_mul_f32 v[104:105], v[164:165], v[104:105]
	v_pk_mul_f32 v[106:107], v[166:167], v[106:107]
	v_pk_fma_f32 v[104:105], v[84:85], v[104:105], v[148:149]
	v_pk_fma_f32 v[106:107], v[86:87], v[106:107], v[150:151]
	v_pk_mul_f32 v[100:101], v[100:101], v[216:217] op_sel_hi:[1,0]
	v_pk_mul_f32 v[102:103], v[102:103], v[216:217] op_sel_hi:[1,0]
	v_pk_mul_f32 v[100:101], v[168:169], v[100:101]
	v_pk_mul_f32 v[102:103], v[170:171], v[102:103]
	v_pk_fma_f32 v[100:101], v[88:89], v[100:101], v[152:153]
	v_pk_fma_f32 v[102:103], v[90:91], v[102:103], v[154:155]
	v_pk_mul_f32 v[96:97], v[96:97], v[216:217] op_sel_hi:[1,0]
	v_pk_mul_f32 v[98:99], v[98:99], v[216:217] op_sel_hi:[1,0]
	v_pk_mul_f32 v[96:97], v[172:173], v[96:97]
	v_pk_mul_f32 v[98:99], v[174:175], v[98:99]
	v_pk_fma_f32 v[96:97], v[92:93], v[96:97], v[156:157]
	v_pk_fma_f32 v[98:99], v[94:95], v[98:99], v[158:159]
	v_cvt_pk_bf16_f32 v236, v108, v109
	v_cvt_pk_bf16_f32 v237, v110, v111
	v_cvt_pk_bf16_f32 v238, v104, v105
	v_cvt_pk_bf16_f32 v239, v106, v107
	s_nop 1
	v_permlane16_swap_b32 v236, v238
	v_permlane16_swap_b32 v237, v239
	global_store_dwordx4 v231, v[236:239], s[62:63] sc1
	v_cvt_pk_bf16_f32 v240, v100, v101
	v_cvt_pk_bf16_f32 v241, v102, v103
	v_cvt_pk_bf16_f32 v242, v96, v97
	v_cvt_pk_bf16_f32 v243, v98, v99
	s_nop 1
	v_permlane16_swap_b32 v240, v242
	v_permlane16_swap_b32 v241, v243
	global_store_dwordx4 v231, v[240:243], s[62:63] offset:256 sc1
	s_add_u32 s62, s54, 0x18000
	s_addc_u32 s63, s55, 0
	v_pk_mul_f32 v[76:77], v[76:77], v[218:219] op_sel_hi:[1,0]
	v_pk_mul_f32 v[78:79], v[78:79], v[218:219] op_sel_hi:[1,0]
	v_pk_mul_f32 v[76:77], v[160:161], v[76:77]
	v_pk_mul_f32 v[78:79], v[162:163], v[78:79]
	v_pk_fma_f32 v[76:77], v[80:81], v[76:77], v[144:145]
	v_pk_fma_f32 v[78:79], v[82:83], v[78:79], v[146:147]
	v_pk_mul_f32 v[72:73], v[72:73], v[218:219] op_sel_hi:[1,0]
	v_pk_mul_f32 v[74:75], v[74:75], v[218:219] op_sel_hi:[1,0]
	v_pk_mul_f32 v[72:73], v[164:165], v[72:73]
	v_pk_mul_f32 v[74:75], v[166:167], v[74:75]
	v_pk_fma_f32 v[72:73], v[84:85], v[72:73], v[148:149]
	v_pk_fma_f32 v[74:75], v[86:87], v[74:75], v[150:151]
	v_pk_mul_f32 v[68:69], v[68:69], v[218:219] op_sel_hi:[1,0]
	v_pk_mul_f32 v[70:71], v[70:71], v[218:219] op_sel_hi:[1,0]
	v_pk_mul_f32 v[68:69], v[168:169], v[68:69]
	v_pk_mul_f32 v[70:71], v[170:171], v[70:71]
	v_pk_fma_f32 v[68:69], v[88:89], v[68:69], v[152:153]
	v_pk_fma_f32 v[70:71], v[90:91], v[70:71], v[154:155]
	v_pk_mul_f32 v[64:65], v[64:65], v[218:219] op_sel_hi:[1,0]
	v_pk_mul_f32 v[66:67], v[66:67], v[218:219] op_sel_hi:[1,0]
	v_pk_mul_f32 v[64:65], v[172:173], v[64:65]
	v_pk_mul_f32 v[66:67], v[174:175], v[66:67]
	v_pk_fma_f32 v[64:65], v[92:93], v[64:65], v[156:157]
	v_pk_fma_f32 v[66:67], v[94:95], v[66:67], v[158:159]
	v_cvt_pk_bf16_f32 v244, v76, v77
	v_cvt_pk_bf16_f32 v245, v78, v79
	v_cvt_pk_bf16_f32 v246, v72, v73
	v_cvt_pk_bf16_f32 v247, v74, v75
	s_nop 1
	v_permlane16_swap_b32 v244, v246
	v_permlane16_swap_b32 v245, v247
	global_store_dwordx4 v231, v[244:247], s[62:63] sc1
	v_cvt_pk_bf16_f32 v248, v68, v69
	v_cvt_pk_bf16_f32 v249, v70, v71
	v_cvt_pk_bf16_f32 v250, v64, v65
	v_cvt_pk_bf16_f32 v251, v66, v67
	s_nop 1
	v_permlane16_swap_b32 v248, v250
	v_permlane16_swap_b32 v249, v251
	global_store_dwordx4 v231, v[248:251], s[62:63] offset:256 sc1
	s_add_u32 s62, s54, 0x40000
	s_addc_u32 s63, s55, 0
	v_pk_mul_f32 v[60:61], v[60:61], v[220:221] op_sel_hi:[1,0]
	v_pk_mul_f32 v[62:63], v[62:63], v[220:221] op_sel_hi:[1,0]
	v_pk_mul_f32 v[60:61], v[160:161], v[60:61]
	v_pk_mul_f32 v[62:63], v[162:163], v[62:63]
	v_pk_fma_f32 v[60:61], v[80:81], v[60:61], v[144:145]
	v_pk_fma_f32 v[62:63], v[82:83], v[62:63], v[146:147]
	v_pk_mul_f32 v[56:57], v[56:57], v[220:221] op_sel_hi:[1,0]
	v_pk_mul_f32 v[58:59], v[58:59], v[220:221] op_sel_hi:[1,0]
	v_pk_mul_f32 v[56:57], v[164:165], v[56:57]
	v_pk_mul_f32 v[58:59], v[166:167], v[58:59]
	v_pk_fma_f32 v[56:57], v[84:85], v[56:57], v[148:149]
	v_pk_fma_f32 v[58:59], v[86:87], v[58:59], v[150:151]
	v_pk_mul_f32 v[52:53], v[52:53], v[220:221] op_sel_hi:[1,0]
	v_pk_mul_f32 v[54:55], v[54:55], v[220:221] op_sel_hi:[1,0]
	v_pk_mul_f32 v[52:53], v[168:169], v[52:53]
	v_pk_mul_f32 v[54:55], v[170:171], v[54:55]
	v_pk_fma_f32 v[52:53], v[88:89], v[52:53], v[152:153]
	v_pk_fma_f32 v[54:55], v[90:91], v[54:55], v[154:155]
	v_pk_mul_f32 v[48:49], v[48:49], v[220:221] op_sel_hi:[1,0]
	v_pk_mul_f32 v[50:51], v[50:51], v[220:221] op_sel_hi:[1,0]
	v_pk_mul_f32 v[48:49], v[172:173], v[48:49]
	v_pk_mul_f32 v[50:51], v[174:175], v[50:51]
	v_pk_fma_f32 v[48:49], v[92:93], v[48:49], v[156:157]
	v_pk_fma_f32 v[50:51], v[94:95], v[50:51], v[158:159]
	v_cvt_pk_bf16_f32 v236, v60, v61
	v_cvt_pk_bf16_f32 v237, v62, v63
	v_cvt_pk_bf16_f32 v238, v56, v57
	v_cvt_pk_bf16_f32 v239, v58, v59
	s_nop 1
	v_permlane16_swap_b32 v236, v238
	v_permlane16_swap_b32 v237, v239
	global_store_dwordx4 v231, v[236:239], s[62:63] sc1
	v_cvt_pk_bf16_f32 v240, v52, v53
	v_cvt_pk_bf16_f32 v241, v54, v55
	v_cvt_pk_bf16_f32 v242, v48, v49
	v_cvt_pk_bf16_f32 v243, v50, v51
	s_nop 1
	v_permlane16_swap_b32 v240, v242
	v_permlane16_swap_b32 v241, v243
	global_store_dwordx4 v231, v[240:243], s[62:63] offset:256 sc1
	s_add_u32 s62, s54, 0x48000
	s_addc_u32 s63, s55, 0
	v_pk_mul_f32 v[44:45], v[44:45], v[222:223] op_sel_hi:[1,0]
	v_pk_mul_f32 v[46:47], v[46:47], v[222:223] op_sel_hi:[1,0]
	v_pk_mul_f32 v[44:45], v[160:161], v[44:45]
	v_pk_mul_f32 v[46:47], v[162:163], v[46:47]
	v_pk_fma_f32 v[44:45], v[80:81], v[44:45], v[144:145]
	v_pk_fma_f32 v[46:47], v[82:83], v[46:47], v[146:147]
	v_pk_mul_f32 v[40:41], v[40:41], v[222:223] op_sel_hi:[1,0]
	v_pk_mul_f32 v[42:43], v[42:43], v[222:223] op_sel_hi:[1,0]
	v_pk_mul_f32 v[40:41], v[164:165], v[40:41]
	v_pk_mul_f32 v[42:43], v[166:167], v[42:43]
	v_pk_fma_f32 v[40:41], v[84:85], v[40:41], v[148:149]
	v_pk_fma_f32 v[42:43], v[86:87], v[42:43], v[150:151]
	v_pk_mul_f32 v[36:37], v[36:37], v[222:223] op_sel_hi:[1,0]
	v_pk_mul_f32 v[38:39], v[38:39], v[222:223] op_sel_hi:[1,0]
	v_pk_mul_f32 v[36:37], v[168:169], v[36:37]
	v_pk_mul_f32 v[38:39], v[170:171], v[38:39]
	v_pk_fma_f32 v[36:37], v[88:89], v[36:37], v[152:153]
	v_pk_fma_f32 v[38:39], v[90:91], v[38:39], v[154:155]
	v_pk_mul_f32 v[32:33], v[32:33], v[222:223] op_sel_hi:[1,0]
	v_pk_mul_f32 v[34:35], v[34:35], v[222:223] op_sel_hi:[1,0]
	v_pk_mul_f32 v[32:33], v[172:173], v[32:33]
	v_pk_mul_f32 v[34:35], v[174:175], v[34:35]
	v_pk_fma_f32 v[32:33], v[92:93], v[32:33], v[156:157]
	v_pk_fma_f32 v[34:35], v[94:95], v[34:35], v[158:159]
	v_cvt_pk_bf16_f32 v244, v44, v45
	v_cvt_pk_bf16_f32 v245, v46, v47
	v_cvt_pk_bf16_f32 v246, v40, v41
	v_cvt_pk_bf16_f32 v247, v42, v43
	s_nop 1
	v_permlane16_swap_b32 v244, v246
	v_permlane16_swap_b32 v245, v247
	global_store_dwordx4 v231, v[244:247], s[62:63] sc1
	v_cvt_pk_bf16_f32 v248, v36, v37
	v_cvt_pk_bf16_f32 v249, v38, v39
	v_cvt_pk_bf16_f32 v250, v32, v33
	v_cvt_pk_bf16_f32 v251, v34, v35
	s_nop 1
	v_permlane16_swap_b32 v248, v250
	v_permlane16_swap_b32 v249, v251
	global_store_dwordx4 v231, v[248:251], s[62:63] offset:256 sc1
	s_add_u32 s62, s54, 0x50000
	s_addc_u32 s63, s55, 0
	v_pk_mul_f32 v[28:29], v[28:29], v[224:225] op_sel_hi:[1,0]
	v_pk_mul_f32 v[30:31], v[30:31], v[224:225] op_sel_hi:[1,0]
	v_pk_mul_f32 v[28:29], v[160:161], v[28:29]
	v_pk_mul_f32 v[30:31], v[162:163], v[30:31]
	v_pk_fma_f32 v[28:29], v[80:81], v[28:29], v[144:145]
	v_pk_fma_f32 v[30:31], v[82:83], v[30:31], v[146:147]
	v_pk_mul_f32 v[24:25], v[24:25], v[224:225] op_sel_hi:[1,0]
	v_pk_mul_f32 v[26:27], v[26:27], v[224:225] op_sel_hi:[1,0]
	v_pk_mul_f32 v[24:25], v[164:165], v[24:25]
	v_pk_mul_f32 v[26:27], v[166:167], v[26:27]
	v_pk_fma_f32 v[24:25], v[84:85], v[24:25], v[148:149]
	v_pk_fma_f32 v[26:27], v[86:87], v[26:27], v[150:151]
	v_pk_mul_f32 v[12:13], v[12:13], v[224:225] op_sel_hi:[1,0]
	v_pk_mul_f32 v[14:15], v[14:15], v[224:225] op_sel_hi:[1,0]
	v_pk_mul_f32 v[12:13], v[168:169], v[12:13]
	v_pk_mul_f32 v[14:15], v[170:171], v[14:15]
	v_pk_fma_f32 v[12:13], v[88:89], v[12:13], v[152:153]
	v_pk_fma_f32 v[14:15], v[90:91], v[14:15], v[154:155]
	v_pk_mul_f32 v[8:9], v[8:9], v[224:225] op_sel_hi:[1,0]
	v_pk_mul_f32 v[10:11], v[10:11], v[224:225] op_sel_hi:[1,0]
	v_pk_mul_f32 v[8:9], v[172:173], v[8:9]
	v_pk_mul_f32 v[10:11], v[174:175], v[10:11]
	v_pk_fma_f32 v[8:9], v[92:93], v[8:9], v[156:157]
	v_pk_fma_f32 v[10:11], v[94:95], v[10:11], v[158:159]
	v_cvt_pk_bf16_f32 v236, v28, v29
	v_cvt_pk_bf16_f32 v237, v30, v31
	v_cvt_pk_bf16_f32 v238, v24, v25
	v_cvt_pk_bf16_f32 v239, v26, v27
	s_nop 1
	v_permlane16_swap_b32 v236, v238
	v_permlane16_swap_b32 v237, v239
	global_store_dwordx4 v231, v[236:239], s[62:63] sc1
	v_cvt_pk_bf16_f32 v240, v12, v13
	v_cvt_pk_bf16_f32 v241, v14, v15
	v_cvt_pk_bf16_f32 v242, v8, v9
	v_cvt_pk_bf16_f32 v243, v10, v11
	s_nop 1
	v_permlane16_swap_b32 v240, v242
	v_permlane16_swap_b32 v241, v243
	global_store_dwordx4 v231, v[240:243], s[62:63] offset:256 sc1
	s_add_u32 s62, s54, 0x58000
	s_addc_u32 s63, s55, 0
	v_pk_mul_f32 v[20:21], v[20:21], v[226:227] op_sel_hi:[1,0]
	v_pk_mul_f32 v[22:23], v[22:23], v[226:227] op_sel_hi:[1,0]
	v_pk_mul_f32 v[20:21], v[160:161], v[20:21]
	v_pk_mul_f32 v[22:23], v[162:163], v[22:23]
	v_pk_fma_f32 v[20:21], v[80:81], v[20:21], v[144:145]
	v_pk_fma_f32 v[22:23], v[82:83], v[22:23], v[146:147]
	v_pk_mul_f32 v[16:17], v[16:17], v[226:227] op_sel_hi:[1,0]
	v_pk_mul_f32 v[18:19], v[18:19], v[226:227] op_sel_hi:[1,0]
	v_pk_mul_f32 v[16:17], v[164:165], v[16:17]
	v_pk_mul_f32 v[18:19], v[166:167], v[18:19]
	v_pk_fma_f32 v[16:17], v[84:85], v[16:17], v[148:149]
	v_pk_fma_f32 v[18:19], v[86:87], v[18:19], v[150:151]
	v_pk_mul_f32 v[4:5], v[4:5], v[226:227] op_sel_hi:[1,0]
	v_pk_mul_f32 v[6:7], v[6:7], v[226:227] op_sel_hi:[1,0]
	v_pk_mul_f32 v[4:5], v[168:169], v[4:5]
	v_pk_mul_f32 v[6:7], v[170:171], v[6:7]
	v_pk_fma_f32 v[4:5], v[88:89], v[4:5], v[152:153]
	v_pk_fma_f32 v[6:7], v[90:91], v[6:7], v[154:155]
	v_pk_mul_f32 v[0:1], v[0:1], v[226:227] op_sel_hi:[1,0]
	v_pk_mul_f32 v[2:3], v[2:3], v[226:227] op_sel_hi:[1,0]
	v_pk_mul_f32 v[0:1], v[172:173], v[0:1]
	v_pk_mul_f32 v[2:3], v[174:175], v[2:3]
	v_pk_fma_f32 v[0:1], v[92:93], v[0:1], v[156:157]
	v_pk_fma_f32 v[2:3], v[94:95], v[2:3], v[158:159]
	v_cvt_pk_bf16_f32 v244, v20, v21
	v_cvt_pk_bf16_f32 v245, v22, v23
	v_cvt_pk_bf16_f32 v246, v16, v17
	v_cvt_pk_bf16_f32 v247, v18, v19
	s_nop 1
	v_permlane16_swap_b32 v244, v246
	v_permlane16_swap_b32 v245, v247
	global_store_dwordx4 v231, v[244:247], s[62:63] sc1
	v_cvt_pk_bf16_f32 v248, v4, v5
	v_cvt_pk_bf16_f32 v249, v6, v7
	v_cvt_pk_bf16_f32 v250, v0, v1
	v_cvt_pk_bf16_f32 v251, v2, v3
	s_nop 1
	v_permlane16_swap_b32 v248, v250
	v_permlane16_swap_b32 v249, v251
	global_store_dwordx4 v231, v[248:251], s[62:63] offset:256 sc1
	v_readlane_b32 s16, v253, 9
	v_readlane_b32 s17, v253, 10
	v_readlane_b32 s34, v254, 63
	v_readlane_b32 s35, v255, 0
	s_waitcnt vmcnt(0)
	s_barrier
	s_and_saveexec_b64 s[0:1], s[34:35]
	s_cbranch_execz .LBB0_1371
	s_add_u32 s98, s98, 1
	v_mov_b32_e32 v7, 0x26c00
	ds_read2_b32 v[8:9], v7 offset1:1
	v_mov_b32_e32 v2, s99
	v_mov_b32_e32 v3, 1
	global_atomic_add v4, v2, v3, s[100:101] sc0
	v_add_u32_e32 v2, 0x1000, v2
	v_mov_b32_e32 v10, 0x2480
	s_waitcnt vmcnt(0) lgkmcnt(0)
	v_add_u32_e32 v4, 1, v4
	v_mul_lo_u32 v5, v8, s98
	v_mul_lo_u32 v9, v9, s98
	v_cmp_eq_u32_e32 vcc, v4, v5
	s_and_saveexec_b64 s[4:5], vcc
	s_cbranch_execz .Lh2_skip_7
	buffer_wbl2 sc1
	s_waitcnt vmcnt(0)
	global_atomic_add v10, v3, s[100:101]
	global_atomic_add v10, v3, s[100:101] offset:256
	global_atomic_add v10, v3, s[100:101] offset:512
	global_atomic_add v10, v3, s[100:101] offset:768
	global_atomic_add v10, v3, s[100:101] offset:1024
	global_atomic_add v10, v3, s[100:101] offset:1280
	global_atomic_add v10, v3, s[100:101] offset:1536
	global_atomic_add v10, v3, s[100:101] offset:1792
	global_atomic_add v10, v3, s[100:101] offset:2048
	global_atomic_add v10, v3, s[100:101] offset:2304
	global_atomic_add v10, v3, s[100:101] offset:2560
	global_atomic_add v10, v3, s[100:101] offset:2816
	global_atomic_add v10, v3, s[100:101] offset:3072
	global_atomic_add v10, v3, s[100:101] offset:3328
	global_atomic_add v10, v3, s[100:101] offset:3584
	global_atomic_add v10, v3, s[100:101] offset:3840
